# mixer phase: the phase's 32 KB of code is re-loaded into L2 at the start of each of its two passes
# baseline (speedup 1.0000x reference)
.LBB0_1193:
	s_getpc_b64 s[98:99]
	v_mbcnt_lo_u32_b32 v254, -1, 0
	v_mbcnt_hi_u32_b32 v254, -1, v254
	v_lshlrev_b32_e32 v254, 9, v254
	global_load_dword v255, v254, s[98:99]
	global_load_dword v255, v254, s[98:99] offset:128
	global_load_dword v255, v254, s[98:99] offset:256
	global_load_dword v255, v254, s[98:99] offset:384
	s_mov_b32 s32, 0
	v_readlane_b32 s8, v252, 7
	v_readlane_b32 s9, v252, 8
	s_and_b64 s[8:9], s[8:9], s[14:15]
	s_and_b64 vcc, exec, s[8:9]
	s_mov_b32 s10, -1
	s_cbranch_vccnz .LBB0_1197
	s_barrier
	s_and_saveexec_b64 s[8:9], s[4:5]
	s_cbranch_execz .LBB0_1196
	s_lshl_b64 s[10:11], s[6:7], 2
	v_readlane_b32 s12, v252, 11
	s_add_u32 s10, s12, s10
	v_readlane_b32 s12, v252, 12
	s_addc_u32 s11, s12, s11
	v_mov_b64_e32 v[4:5], s[10:11]
	flat_atomic_add v4, v[4:5], v177 sc0
	s_waitcnt vmcnt(0) lgkmcnt(0)
	ds_write_b32 v178, v4

.LBB0_2950:
	s_getpc_b64 s[98:99]
	v_mbcnt_lo_u32_b32 v254, -1, 0
	v_mbcnt_hi_u32_b32 v254, -1, v254
	v_lshlrev_b32_e32 v254, 9, v254
	global_load_dword v255, v254, s[98:99]
	global_load_dword v255, v254, s[98:99] offset:128
	global_load_dword v255, v254, s[98:99] offset:256
	global_load_dword v255, v254, s[98:99] offset:384
	s_mov_b32 s32, 0
	v_readlane_b32 s8, v252, 7
	v_readlane_b32 s9, v252, 8
	s_and_b64 s[8:9], s[8:9], s[14:15]
	s_and_b64 vcc, exec, s[8:9]
	s_mov_b32 s10, -1
	s_cbranch_vccnz .LBB0_2954
	s_barrier
	s_and_saveexec_b64 s[8:9], s[4:5]
	s_cbranch_execz .LBB0_2953
	s_lshl_b64 s[10:11], s[6:7], 2
	v_readlane_b32 s12, v252, 11
	s_add_u32 s10, s12, s10
	v_readlane_b32 s12, v252, 12
	s_addc_u32 s11, s12, s11
	v_mov_b64_e32 v[4:5], s[10:11]
	flat_atomic_add v4, v[4:5], v176 sc0
	s_waitcnt vmcnt(0) lgkmcnt(0)
	ds_write_b32 v177, v4
